# diff attention near tiles: sixteen exec-masked serialized T5-bias LDS lookups per map replaced by straight-line code with eight lookups in flight
# baseline (speedup 1.0000x reference)
.LBB0_530:
	s_add_i32 s10, s25, s28
	s_cmp_gt_i32 s10, s26
	s_cbranch_scc1 .LBB0_527
	v_mov_b32_e32 v128, s67
	v_add3_u32 v216, s20, v246, v192
	ds_read_b32 v251, v128
	ds_read_b128 v[160:163], v216
	ds_read_b128 v[164:167], v240
	ds_read_b128 v[168:171], v216 offset:32
	ds_read_b128 v[172:175], v240 offset:32
	ds_read_b128 v[128:131], v216 offset:64
	ds_read_b128 v[132:135], v240 offset:64
	ds_read_b128 v[136:139], v216 offset:96
	ds_read_b128 v[140:143], v240 offset:96
	s_cmpk_gt_i32 s27, 0x7f
	s_cselect_b64 s[10:11], -1, 0
	s_cmpk_lt_i32 s27, 0x80
	v_add_u32_e32 v252, s27, v249
	s_cselect_b64 s[18:19], -1, 0
	s_and_b64 vcc, exec, s[10:11]
	v_add_u32_e32 v253, 63, v252
	s_waitcnt lgkmcnt(6)
	v_mfma_f32_32x32x16_bf16 v[144:159], v[160:163], v[164:167], 0
	ds_read_b128 v[160:163], v216 offset:128
	ds_read_b128 v[164:167], v240 offset:128
	s_waitcnt lgkmcnt(6)
	v_mfma_f32_32x32x16_bf16 v[144:159], v[168:171], v[172:175], v[144:159]
	ds_read_b128 v[168:171], v216 offset:160
	ds_read_b128 v[172:175], v240 offset:160
	s_waitcnt lgkmcnt(6)
	v_mfma_f32_32x32x16_bf16 v[144:159], v[128:131], v[132:135], v[144:159]
	s_waitcnt lgkmcnt(4)
	v_mfma_f32_32x32x16_bf16 v[144:159], v[136:139], v[140:143], v[144:159]
	s_waitcnt lgkmcnt(2)
	v_mfma_f32_32x32x16_bf16 v[128:143], v[160:163], v[164:167], 0
	ds_read_b128 v[160:163], v216 offset:192
	ds_read_b128 v[164:167], v240 offset:192
	s_waitcnt lgkmcnt(2)
	v_mfma_f32_32x32x16_bf16 v[128:143], v[168:171], v[172:175], v[128:143]
	ds_read_b128 v[168:171], v216 offset:224
	ds_read_b128 v[172:175], v240 offset:224
	s_waitcnt lgkmcnt(2)
	v_mfma_f32_32x32x16_bf16 v[128:143], v[160:163], v[164:167], v[128:143]
	s_waitcnt lgkmcnt(0)
	v_mfma_f32_32x32x16_bf16 v[128:143], v[168:171], v[172:175], v[128:143]
	s_nop 1
	s_cbranch_vccnz .LBB0_565
	s_mov_b32 s99, 0x12800
	v_mov_b32_e32 v217, 0xff800000
	v_max_i32_e32 v160, 0, v253
	v_min_u32_e32 v160, 0x80, v160
	v_lshl_add_u32 v160, v160, 2, s99
	ds_read_b32 v160, v160
	v_add_u32_e32 v161, 62, v252
	v_max_i32_e32 v161, 0, v161
	v_min_u32_e32 v161, 0x80, v161
	v_lshl_add_u32 v161, v161, 2, s99
	ds_read_b32 v161, v161
	v_add_u32_e32 v162, 61, v252
	v_max_i32_e32 v162, 0, v162
	v_min_u32_e32 v162, 0x80, v162
	v_lshl_add_u32 v162, v162, 2, s99
	ds_read_b32 v162, v162
	v_add_u32_e32 v163, 60, v252
	v_max_i32_e32 v163, 0, v163
	v_min_u32_e32 v163, 0x80, v163
	v_lshl_add_u32 v163, v163, 2, s99
	ds_read_b32 v163, v163
	v_add_u32_e32 v164, 55, v252
	v_max_i32_e32 v164, 0, v164
	v_min_u32_e32 v164, 0x80, v164
	v_lshl_add_u32 v164, v164, 2, s99
	ds_read_b32 v164, v164
	v_add_u32_e32 v165, 54, v252
	v_max_i32_e32 v165, 0, v165
	v_min_u32_e32 v165, 0x80, v165
	v_lshl_add_u32 v165, v165, 2, s99
	ds_read_b32 v165, v165
	v_add_u32_e32 v166, 53, v252
	v_max_i32_e32 v166, 0, v166
	v_min_u32_e32 v166, 0x80, v166
	v_lshl_add_u32 v166, v166, 2, s99
	ds_read_b32 v166, v166
	v_add_u32_e32 v167, 52, v252
	v_max_i32_e32 v167, 0, v167
	v_min_u32_e32 v167, 0x80, v167
	v_lshl_add_u32 v167, v167, 2, s99
	ds_read_b32 v167, v167
	s_waitcnt lgkmcnt(7)
	v_fmac_f32_e32 v160, 0x3e38aa3b, v144
	v_cmp_le_i32_e32 vcc, 0xffffffc1, v252
	s_nop 1
	v_cndmask_b32_e32 v144, v217, v160, vcc
	s_waitcnt lgkmcnt(6)
	v_fmac_f32_e32 v161, 0x3e38aa3b, v145
	v_cmp_le_i32_e32 vcc, 0xffffffc2, v252
	s_nop 1
	v_cndmask_b32_e32 v145, v217, v161, vcc
	s_waitcnt lgkmcnt(5)
	v_fmac_f32_e32 v162, 0x3e38aa3b, v146
	v_cmp_le_i32_e32 vcc, 0xffffffc3, v252
	s_nop 1
	v_cndmask_b32_e32 v146, v217, v162, vcc
	s_waitcnt lgkmcnt(4)
	v_fmac_f32_e32 v163, 0x3e38aa3b, v147
	v_cmp_le_i32_e32 vcc, 0xffffffc4, v252
	s_nop 1
	v_cndmask_b32_e32 v147, v217, v163, vcc
	s_waitcnt lgkmcnt(3)
	v_fmac_f32_e32 v164, 0x3e38aa3b, v148
	v_cmp_le_i32_e32 vcc, 0xffffffc9, v252
	s_nop 1
	v_cndmask_b32_e32 v148, v217, v164, vcc
	s_waitcnt lgkmcnt(2)
	v_fmac_f32_e32 v165, 0x3e38aa3b, v149
	v_cmp_le_i32_e32 vcc, 0xffffffca, v252
	s_nop 1
	v_cndmask_b32_e32 v149, v217, v165, vcc
	s_waitcnt lgkmcnt(1)
	v_fmac_f32_e32 v166, 0x3e38aa3b, v150
	v_cmp_le_i32_e32 vcc, 0xffffffcb, v252
	s_nop 1
	v_cndmask_b32_e32 v150, v217, v166, vcc
	s_waitcnt lgkmcnt(0)
	v_fmac_f32_e32 v167, 0x3e38aa3b, v151
	v_cmp_le_i32_e32 vcc, 0xffffffcc, v252
	s_nop 1
	v_cndmask_b32_e32 v151, v217, v167, vcc
	v_add_u32_e32 v168, 47, v252
	v_max_i32_e32 v168, 0, v168
	v_min_u32_e32 v168, 0x80, v168
	v_lshl_add_u32 v168, v168, 2, s99
	ds_read_b32 v168, v168
	v_add_u32_e32 v169, 46, v252
	v_max_i32_e32 v169, 0, v169
	v_min_u32_e32 v169, 0x80, v169
	v_lshl_add_u32 v169, v169, 2, s99
	ds_read_b32 v169, v169
	v_add_u32_e32 v170, 45, v252
	v_max_i32_e32 v170, 0, v170
	v_min_u32_e32 v170, 0x80, v170
	v_lshl_add_u32 v170, v170, 2, s99
	ds_read_b32 v170, v170
	v_add_u32_e32 v171, 44, v252
	v_max_i32_e32 v171, 0, v171
	v_min_u32_e32 v171, 0x80, v171
	v_lshl_add_u32 v171, v171, 2, s99
	ds_read_b32 v171, v171
	v_add_u32_e32 v172, 39, v252
	v_max_i32_e32 v172, 0, v172
	v_min_u32_e32 v172, 0x80, v172
	v_lshl_add_u32 v172, v172, 2, s99
	ds_read_b32 v172, v172
	v_add_u32_e32 v173, 38, v252
	v_max_i32_e32 v173, 0, v173
	v_min_u32_e32 v173, 0x80, v173
	v_lshl_add_u32 v173, v173, 2, s99
	ds_read_b32 v173, v173
	v_add_u32_e32 v174, 37, v252
	v_max_i32_e32 v174, 0, v174
	v_min_u32_e32 v174, 0x80, v174
	v_lshl_add_u32 v174, v174, 2, s99
	ds_read_b32 v174, v174
	v_add_u32_e32 v175, 36, v252
	v_max_i32_e32 v175, 0, v175
	v_min_u32_e32 v175, 0x80, v175
	v_lshl_add_u32 v175, v175, 2, s99
	ds_read_b32 v175, v175
	s_waitcnt lgkmcnt(7)
	v_fmac_f32_e32 v168, 0x3e38aa3b, v152
	v_cmp_le_i32_e32 vcc, 0xffffffd1, v252
	s_nop 1
	v_cndmask_b32_e32 v152, v217, v168, vcc
	s_waitcnt lgkmcnt(6)
	v_fmac_f32_e32 v169, 0x3e38aa3b, v153
	v_cmp_le_i32_e32 vcc, 0xffffffd2, v252
	s_nop 1
	v_cndmask_b32_e32 v153, v217, v169, vcc
	s_waitcnt lgkmcnt(5)
	v_fmac_f32_e32 v170, 0x3e38aa3b, v154
	v_cmp_le_i32_e32 vcc, 0xffffffd3, v252
	s_nop 1
	v_cndmask_b32_e32 v154, v217, v170, vcc
	s_waitcnt lgkmcnt(4)
	v_fmac_f32_e32 v171, 0x3e38aa3b, v155
	v_cmp_le_i32_e32 vcc, 0xffffffd4, v252
	s_nop 1
	v_cndmask_b32_e32 v155, v217, v171, vcc
	s_waitcnt lgkmcnt(3)
	v_fmac_f32_e32 v172, 0x3e38aa3b, v156
	v_cmp_le_i32_e32 vcc, 0xffffffd9, v252
	s_nop 1
	v_cndmask_b32_e32 v156, v217, v172, vcc
	s_waitcnt lgkmcnt(2)
	v_fmac_f32_e32 v173, 0x3e38aa3b, v157
	v_cmp_le_i32_e32 vcc, 0xffffffda, v252
	s_nop 1
	v_cndmask_b32_e32 v157, v217, v173, vcc
	s_waitcnt lgkmcnt(1)
	v_fmac_f32_e32 v174, 0x3e38aa3b, v158
	v_cmp_le_i32_e32 vcc, 0xffffffdb, v252
	s_nop 1
	v_cndmask_b32_e32 v158, v217, v174, vcc
	s_waitcnt lgkmcnt(0)
	v_fmac_f32_e32 v175, 0x3e38aa3b, v159
	v_cmp_le_i32_e32 vcc, 0xffffffdc, v252
	s_nop 1
	v_cndmask_b32_e32 v159, v217, v175, vcc

.LBB0_567:
	v_mov_b32_e32 v160, 0x3e38aa3b
	v_cndmask_b32_e64 v162, 0, v251, s[10:11]
	v_cndmask_b32_e64 v161, 1.0, v160, s[10:11]
	v_sub_f32_e32 v160, v162, v250
	v_fma_f32 v144, v161, v144, v160
	v_exp_f32_e32 v163, v144
	v_fma_f32 v144, v161, v145, v160
	v_exp_f32_e32 v164, v144
	v_fma_f32 v144, v161, v146, v160
	v_exp_f32_e32 v165, v144
	v_fma_f32 v144, v161, v147, v160
	v_exp_f32_e32 v166, v144
	v_fma_f32 v144, v161, v148, v160
	v_exp_f32_e32 v167, v144
	v_fma_f32 v144, v161, v149, v160
	v_exp_f32_e32 v168, v144
	v_fma_f32 v144, v161, v150, v160
	v_exp_f32_e32 v169, v144
	v_fma_f32 v144, v161, v151, v160
	v_exp_f32_e32 v171, v144
	v_fma_f32 v144, v161, v152, v160
	v_exp_f32_e32 v170, v144
	v_fma_f32 v144, v161, v153, v160
	v_exp_f32_e32 v172, v144
	v_fma_f32 v144, v161, v154, v160
	v_exp_f32_e32 v173, v144
	v_fma_f32 v144, v161, v155, v160
	v_exp_f32_e32 v174, v144
	v_fma_f32 v144, v161, v156, v160
	v_exp_f32_e32 v175, v144
	v_fma_f32 v144, v161, v157, v160
	v_exp_f32_e32 v217, v144
	v_fma_f32 v144, v161, v158, v160
	v_fmac_f32_e32 v160, v161, v159
	v_add_u32_e32 v152, s30, v247
	v_exp_f32_e32 v216, v160
	v_add_u32_e32 v160, v152, v248
	ds_read_b64_tr_b16 v[152:153], v160 offset:34816
	ds_read_b64_tr_b16 v[154:155], v160 offset:37376
	v_cvt_pk_bf16_f32 v148, v163, v164
	v_cvt_pk_bf16_f32 v149, v165, v166
	v_cvt_pk_bf16_f32 v150, v167, v168
	v_cvt_pk_bf16_f32 v151, v169, v171
	v_exp_f32_e32 v215, v144
	v_cvt_pk_bf16_f32 v144, v170, v172
	v_cvt_pk_bf16_f32 v145, v173, v174
	v_cvt_pk_bf16_f32 v146, v175, v217
	v_cvt_pk_bf16_f32 v147, v215, v216
	v_add_f32_e32 v156, v163, v164
	v_add_f32_e32 v157, v165, v166
	v_add_f32_e32 v156, v156, v157
	v_add_f32_e32 v157, v167, v168
	v_add_f32_e32 v158, v169, v171
	v_add_f32_e32 v157, v157, v158
	v_add_f32_e32 v156, v156, v157
	v_add_f32_e32 v157, v170, v172
	v_add_f32_e32 v158, v173, v174
	v_add_f32_e32 v157, v157, v158
	v_add_f32_e32 v158, v175, v217
	v_add_f32_e32 v159, v215, v216
	v_add_f32_e32 v158, v158, v159
	v_add_f32_e32 v157, v157, v158
	v_add_f32_e32 v156, v156, v157
	v_add_f32_e32 v209, v209, v156
	s_andn2_b64 vcc, exec, s[18:19]
	ds_read_b64_tr_b16 v[156:157], v160 offset:34880
	ds_read_b64_tr_b16 v[158:159], v160 offset:37440
	ds_read_b64_tr_b16 v[164:165], v160 offset:34944
	ds_read_b64_tr_b16 v[166:167], v160 offset:37504
	ds_read_b64_tr_b16 v[168:169], v160 offset:35008
	ds_read_b64_tr_b16 v[170:171], v160 offset:37568
	s_waitcnt lgkmcnt(6)
	v_mfma_f32_32x32x16_bf16 v[112:127], v[152:155], v[148:151], v[112:127]
	ds_read_b64_tr_b16 v[152:153], v160 offset:39936
	ds_read_b64_tr_b16 v[154:155], v160 offset:42496
	s_waitcnt lgkmcnt(6)
	v_mfma_f32_32x32x16_bf16 v[64:79], v[156:159], v[148:151], v[64:79]
	ds_read_b64_tr_b16 v[156:157], v160 offset:40000
	ds_read_b64_tr_b16 v[158:159], v160 offset:42560
	s_waitcnt lgkmcnt(6)
	v_mfma_f32_32x32x16_bf16 v[32:47], v[164:167], v[148:151], v[32:47]
	ds_read_b64_tr_b16 v[164:165], v160 offset:40064
	ds_read_b64_tr_b16 v[166:167], v160 offset:42624
	s_waitcnt lgkmcnt(6)
	v_mfma_f32_32x32x16_bf16 v[0:15], v[168:171], v[148:151], v[0:15]
	ds_read_b64_tr_b16 v[168:169], v160 offset:40128
	ds_read_b64_tr_b16 v[170:171], v160 offset:42688
	s_waitcnt lgkmcnt(6)
	v_mfma_f32_32x32x16_bf16 v[112:127], v[152:155], v[144:147], v[112:127]
	s_waitcnt lgkmcnt(4)
	v_mfma_f32_32x32x16_bf16 v[64:79], v[156:159], v[144:147], v[64:79]
	s_waitcnt lgkmcnt(2)
	v_mfma_f32_32x32x16_bf16 v[32:47], v[164:167], v[144:147], v[32:47]
	s_waitcnt lgkmcnt(0)
	v_mfma_f32_32x32x16_bf16 v[0:15], v[168:171], v[144:147], v[0:15]
	s_cbranch_vccnz .LBB0_601
	s_mov_b32 s99, 0x12800
	v_mov_b32_e32 v163, 0xff800000
	v_max_i32_e32 v144, 0, v253
	v_min_u32_e32 v144, 0x80, v144
	v_lshl_add_u32 v144, v144, 2, s99
	ds_read_b32 v144, v144
	v_add_u32_e32 v145, 62, v252
	v_max_i32_e32 v145, 0, v145
	v_min_u32_e32 v145, 0x80, v145
	v_lshl_add_u32 v145, v145, 2, s99
	ds_read_b32 v145, v145
	v_add_u32_e32 v146, 61, v252
	v_max_i32_e32 v146, 0, v146
	v_min_u32_e32 v146, 0x80, v146
	v_lshl_add_u32 v146, v146, 2, s99
	ds_read_b32 v146, v146
	v_add_u32_e32 v147, 60, v252
	v_max_i32_e32 v147, 0, v147
	v_min_u32_e32 v147, 0x80, v147
	v_lshl_add_u32 v147, v147, 2, s99
	ds_read_b32 v147, v147
	v_add_u32_e32 v148, 55, v252
	v_max_i32_e32 v148, 0, v148
	v_min_u32_e32 v148, 0x80, v148
	v_lshl_add_u32 v148, v148, 2, s99
	ds_read_b32 v148, v148
	v_add_u32_e32 v149, 54, v252
	v_max_i32_e32 v149, 0, v149
	v_min_u32_e32 v149, 0x80, v149
	v_lshl_add_u32 v149, v149, 2, s99
	ds_read_b32 v149, v149
	v_add_u32_e32 v150, 53, v252
	v_max_i32_e32 v150, 0, v150
	v_min_u32_e32 v150, 0x80, v150
	v_lshl_add_u32 v150, v150, 2, s99
	ds_read_b32 v150, v150
	v_add_u32_e32 v151, 52, v252
	v_max_i32_e32 v151, 0, v151
	v_min_u32_e32 v151, 0x80, v151
	v_lshl_add_u32 v151, v151, 2, s99
	ds_read_b32 v151, v151
	s_waitcnt lgkmcnt(7)
	v_fmac_f32_e32 v144, 0x3e38aa3b, v128
	v_cmp_le_i32_e32 vcc, 0xffffffc1, v252
	s_nop 1
	v_cndmask_b32_e32 v128, v163, v144, vcc
	s_waitcnt lgkmcnt(6)
	v_fmac_f32_e32 v145, 0x3e38aa3b, v129
	v_cmp_le_i32_e32 vcc, 0xffffffc2, v252
	s_nop 1
	v_cndmask_b32_e32 v129, v163, v145, vcc
	s_waitcnt lgkmcnt(5)
	v_fmac_f32_e32 v146, 0x3e38aa3b, v130
	v_cmp_le_i32_e32 vcc, 0xffffffc3, v252
	s_nop 1
	v_cndmask_b32_e32 v130, v163, v146, vcc
	s_waitcnt lgkmcnt(4)
	v_fmac_f32_e32 v147, 0x3e38aa3b, v131
	v_cmp_le_i32_e32 vcc, 0xffffffc4, v252
	s_nop 1
	v_cndmask_b32_e32 v131, v163, v147, vcc
	s_waitcnt lgkmcnt(3)
	v_fmac_f32_e32 v148, 0x3e38aa3b, v132
	v_cmp_le_i32_e32 vcc, 0xffffffc9, v252
	s_nop 1
	v_cndmask_b32_e32 v132, v163, v148, vcc
	s_waitcnt lgkmcnt(2)
	v_fmac_f32_e32 v149, 0x3e38aa3b, v133
	v_cmp_le_i32_e32 vcc, 0xffffffca, v252
	s_nop 1
	v_cndmask_b32_e32 v133, v163, v149, vcc
	s_waitcnt lgkmcnt(1)
	v_fmac_f32_e32 v150, 0x3e38aa3b, v134
	v_cmp_le_i32_e32 vcc, 0xffffffcb, v252
	s_nop 1
	v_cndmask_b32_e32 v134, v163, v150, vcc
	s_waitcnt lgkmcnt(0)
	v_fmac_f32_e32 v151, 0x3e38aa3b, v135
	v_cmp_le_i32_e32 vcc, 0xffffffcc, v252
	s_nop 1
	v_cndmask_b32_e32 v135, v163, v151, vcc
	v_add_u32_e32 v152, 47, v252
	v_max_i32_e32 v152, 0, v152
	v_min_u32_e32 v152, 0x80, v152
	v_lshl_add_u32 v152, v152, 2, s99
	ds_read_b32 v152, v152
	v_add_u32_e32 v153, 46, v252
	v_max_i32_e32 v153, 0, v153
	v_min_u32_e32 v153, 0x80, v153
	v_lshl_add_u32 v153, v153, 2, s99
	ds_read_b32 v153, v153
	v_add_u32_e32 v154, 45, v252
	v_max_i32_e32 v154, 0, v154
	v_min_u32_e32 v154, 0x80, v154
	v_lshl_add_u32 v154, v154, 2, s99
	ds_read_b32 v154, v154
	v_add_u32_e32 v155, 44, v252
	v_max_i32_e32 v155, 0, v155
	v_min_u32_e32 v155, 0x80, v155
	v_lshl_add_u32 v155, v155, 2, s99
	ds_read_b32 v155, v155
	v_add_u32_e32 v156, 39, v252
	v_max_i32_e32 v156, 0, v156
	v_min_u32_e32 v156, 0x80, v156
	v_lshl_add_u32 v156, v156, 2, s99
	ds_read_b32 v156, v156
	v_add_u32_e32 v157, 38, v252
	v_max_i32_e32 v157, 0, v157
	v_min_u32_e32 v157, 0x80, v157
	v_lshl_add_u32 v157, v157, 2, s99
	ds_read_b32 v157, v157
	v_add_u32_e32 v158, 37, v252
	v_max_i32_e32 v158, 0, v158
	v_min_u32_e32 v158, 0x80, v158
	v_lshl_add_u32 v158, v158, 2, s99
	ds_read_b32 v158, v158
	v_add_u32_e32 v159, 36, v252
	v_max_i32_e32 v159, 0, v159
	v_min_u32_e32 v159, 0x80, v159
	v_lshl_add_u32 v159, v159, 2, s99
	ds_read_b32 v159, v159
	s_waitcnt lgkmcnt(7)
	v_fmac_f32_e32 v152, 0x3e38aa3b, v136
	v_cmp_le_i32_e32 vcc, 0xffffffd1, v252
	s_nop 1
	v_cndmask_b32_e32 v136, v163, v152, vcc
	s_waitcnt lgkmcnt(6)
	v_fmac_f32_e32 v153, 0x3e38aa3b, v137
	v_cmp_le_i32_e32 vcc, 0xffffffd2, v252
	s_nop 1
	v_cndmask_b32_e32 v137, v163, v153, vcc
	s_waitcnt lgkmcnt(5)
	v_fmac_f32_e32 v154, 0x3e38aa3b, v138
	v_cmp_le_i32_e32 vcc, 0xffffffd3, v252
	s_nop 1
	v_cndmask_b32_e32 v138, v163, v154, vcc
	s_waitcnt lgkmcnt(4)
	v_fmac_f32_e32 v155, 0x3e38aa3b, v139
	v_cmp_le_i32_e32 vcc, 0xffffffd4, v252
	s_nop 1
	v_cndmask_b32_e32 v139, v163, v155, vcc
	s_waitcnt lgkmcnt(3)
	v_fmac_f32_e32 v156, 0x3e38aa3b, v140
	v_cmp_le_i32_e32 vcc, 0xffffffd9, v252
	s_nop 1
	v_cndmask_b32_e32 v140, v163, v156, vcc
	s_waitcnt lgkmcnt(2)
	v_fmac_f32_e32 v157, 0x3e38aa3b, v141
	v_cmp_le_i32_e32 vcc, 0xffffffda, v252
	s_nop 1
	v_cndmask_b32_e32 v141, v163, v157, vcc
	s_waitcnt lgkmcnt(1)
	v_fmac_f32_e32 v158, 0x3e38aa3b, v142
	v_cmp_le_i32_e32 vcc, 0xffffffdb, v252
	s_nop 1
	v_cndmask_b32_e32 v142, v163, v158, vcc
	s_waitcnt lgkmcnt(0)
	v_fmac_f32_e32 v159, 0x3e38aa3b, v143
	v_cmp_le_i32_e32 vcc, 0xffffffdc, v252
	s_nop 1
	v_cndmask_b32_e32 v143, v163, v159, vcc
